# attention: fold softmax scale into bias/exp FMAs (drops 20 v_pk_mul per unit), on top of v79
# speedup vs baseline: 1.0022x; 1.0022x over previous
; #define LAS __attribute__((address_space(3)))
; __device__ __forceinline__ void attn_phase(const Params& p, LAS unsigned char* lds, int tid, int G, int bid) {
;     ...
;         for (int tt = 0; tt < 10; ++tt) { const LAS unsigned char* kp = lds + (16 * (tstart + tt) + fr) * KS_PITCH + quad * 8;
;             const long k0 = *(const LAS long*)kp, k1 = *(const LAS long*)(kp + 32);
;             f32x4 a = {0.f, 0.f, 0.f, 0.f};
;             a = __builtin_amdgcn_mfma_f32_16x16x32_fp8_fp8(k0, q0, a, 0, 0, 0);
;             s[tt] = __builtin_amdgcn_mfma_f32_16x16x32_fp8_fp8(k1, q1, a, 0, 0, 0) * C2; }
;         const float sl2 = __builtin_amdgcn_exp2f(-8.0f * (float)(head + 1) / 12.0f) * (float)d * LOG2E;
;         float mx = -INFINITY;
; #pragma unroll
;         for (int tt = 0; tt < 10; ++tt)
; #pragma unroll
;             for (int j = 0; j < 4; ++j) { const int kj = 16 * (tstart + tt) + 4 * quad + j, delta = qi + 128 - kj;
;                 const bool valid = (delta >= 0) && (delta <= 128) && (nb > 0 || kj >= 128);
;                 const float v = valid ? s[tt][j] - sl2 * (float)delta : -INFINITY; s[tt][j] = v; mx = fmaxf(mx, v); }
.LBB0_284:
	ds_read2_b64 v[214:217], v169 offset1:4
	ds_read2_b64 v[218:221], v171 offset1:4
	ds_read2_b64 v[222:225], v172 offset1:4
	ds_read2_b64 v[226:229], v173 offset1:4
	ds_read2_b64 v[230:233], v174 offset1:4
	ds_read2_b64 v[234:237], v175 offset1:4
	ds_read2_b64 v[238:241], v176 offset1:4
	ds_read2_b64 v[242:245], v177 offset1:4
	ds_read2_b64 v[186:189], v178 offset1:4
	ds_read2_b64 v[252:255], v179 offset1:4
	s_mul_hi_i32 s0, s11, 0x2aaaaaab
	s_lshr_b32 s1, s0, 31
	s_ashr_i32 s0, s0, 5
	s_add_i32 s0, s0, s1
	s_mul_i32 s1, s0, 0xffffff40
	s_add_i32 s1, s11, s1
	s_ashr_i32 s4, s1, 6
	s_and_b32 s6, s11, 15
	s_lshl_b32 s7, s4, 2
	s_bfe_u32 s11, s11, 0x20004
	s_or_b32 s7, s11, s7
	s_add_i32 s7, s7, 1
	v_cvt_f32_i32_e32 v9, s7
	s_lshl_b32 s1, s4, 1
	s_lshl_b32 s5, -1, s1
	s_andn2_b32 s5, s6, s5
	v_mul_f32_e32 v9, 0xc1000000, v9
	s_lshr_b32 s86, s6, s1
	s_lshl_b32 s6, 1, s1
	s_cmp_lg_u32 s86, 0
	s_waitcnt lgkmcnt(9)
	v_mfma_f32_16x16x32_fp8_fp8 v[68:71], v[214:215], v[62:63], 0
	v_mfma_f32_16x16x32_fp8_fp8 v[214:217], v[216:217], v[60:61], v[68:71]
	s_waitcnt lgkmcnt(8)
	v_mfma_f32_16x16x32_fp8_fp8 v[190:193], v[218:219], v[62:63], 0
	v_mfma_f32_16x16x32_fp8_fp8 v[218:221], v[220:221], v[60:61], v[190:193]
	s_waitcnt lgkmcnt(7)
	v_mfma_f32_16x16x32_fp8_fp8 v[68:71], v[222:223], v[62:63], 0
	v_mfma_f32_16x16x32_fp8_fp8 v[222:225], v[224:225], v[60:61], v[68:71]
	s_waitcnt lgkmcnt(6)
	v_mfma_f32_16x16x32_fp8_fp8 v[190:193], v[226:227], v[62:63], 0
	v_mfma_f32_16x16x32_fp8_fp8 v[226:229], v[228:229], v[60:61], v[190:193]
	s_waitcnt lgkmcnt(5)
	v_mfma_f32_16x16x32_fp8_fp8 v[68:71], v[230:231], v[62:63], 0
	v_mfma_f32_16x16x32_fp8_fp8 v[230:233], v[232:233], v[60:61], v[68:71]
	s_waitcnt lgkmcnt(4)
	v_mfma_f32_16x16x32_fp8_fp8 v[190:193], v[234:235], v[62:63], 0
	v_mfma_f32_16x16x32_fp8_fp8 v[234:237], v[236:237], v[60:61], v[190:193]
	s_waitcnt lgkmcnt(3)
	v_mfma_f32_16x16x32_fp8_fp8 v[68:71], v[238:239], v[62:63], 0
	v_mfma_f32_16x16x32_fp8_fp8 v[238:241], v[240:241], v[60:61], v[68:71]
	s_waitcnt lgkmcnt(2)
	v_mfma_f32_16x16x32_fp8_fp8 v[190:193], v[242:243], v[62:63], 0
	v_mfma_f32_16x16x32_fp8_fp8 v[242:245], v[244:245], v[60:61], v[190:193]
	s_waitcnt lgkmcnt(1)
	v_mfma_f32_16x16x32_fp8_fp8 v[68:71], v[186:187], v[62:63], 0
	v_mfma_f32_16x16x32_fp8_fp8 v[186:189], v[188:189], v[60:61], v[68:71]
	s_waitcnt lgkmcnt(0)
	v_mfma_f32_16x16x32_fp8_fp8 v[190:193], v[252:253], v[62:63], 0
	v_mfma_f32_16x16x32_fp8_fp8 v[252:255], v[254:255], v[60:61], v[190:193]
	v_div_scale_f32 v62, vcc, s3, s3, v9
	v_rcp_f32_e32 v63, v62
	s_nop 0
	v_fma_f32 v104, -v62, v63, 1.0
	v_fmac_f32_e32 v63, v104, v63
	v_div_scale_f32 v104, vcc, v9, s3, v9
	v_mul_f32_e32 v105, v104, v63
	v_fma_f32 v106, -v62, v105, v104
	v_fmac_f32_e32 v105, v106, v63
	v_fma_f32 v62, -v62, v105, v104
	v_div_fmas_f32 v62, v62, v63, v105
	v_div_fixup_f32 v9, v62, s3, v9
	v_exp_f32_e32 v9, v9
	v_cvt_f32_u32_e32 v62, s6
	s_cselect_b64 s[6:7], -1, 0
	v_mul_f32_e32 v9, v9, v62
	v_mul_f32_e32 v9, 0xc1000000, v9
	v_fma_f32 v62, v9, v125, v214
	v_fma_f32 v63, v9, v126, v215
	v_fma_f32 v116, v9, v127, v216
	v_fma_f32 v117, v9, v128, v217
	v_fma_f32 v114, v9, v129, v218
	v_fma_f32 v115, v9, v130, v219
	v_fma_f32 v112, v9, v131, v220
	v_fma_f32 v113, v9, v132, v221
	v_fma_f32 v110, v9, v133, v222
	v_fma_f32 v111, v9, v134, v223
	v_fma_f32 v108, v9, v135, v224
	v_fma_f32 v109, v9, v136, v225
	v_fma_f32 v106, v9, v137, v226
	v_fma_f32 v107, v9, v138, v227
	v_fma_f32 v104, v9, v139, v228
	v_fma_f32 v105, v9, v140, v229
	v_fma_f32 v82, v9, v141, v230
	v_fma_f32 v83, v9, v142, v231
	v_fma_f32 v80, v9, v143, v232
	v_fma_f32 v81, v9, v145, v233
	v_fma_f32 v78, v9, v146, v234
	v_fma_f32 v79, v9, v147, v235
	v_fma_f32 v76, v9, v148, v236
	v_fma_f32 v77, v9, v149, v237
	v_fma_f32 v74, v9, v150, v238
	v_fma_f32 v75, v9, v151, v239
	v_fma_f32 v72, v9, v152, v240
	v_fma_f32 v73, v9, v153, v241
	v_fma_f32 v70, v9, v154, v242
	v_fma_f32 v71, v9, v155, v243
	v_fma_f32 v68, v9, v156, v244
	v_fma_f32 v69, v9, v157, v245
	v_fma_f32 v66, v9, v158, v186
	v_fma_f32 v67, v9, v159, v187
	v_fma_f32 v64, v9, v160, v188
	v_fma_f32 v65, v9, v161, v189
	v_fma_f32 v60, v9, v162, v252
	v_fma_f32 v61, v9, v163, v253
	v_fma_f32 v10, v9, v164, v254
	v_fma_f32 v11, v9, v165, v255
	s_cmp_lg_u32 s6, 0
	s_cbranch_scc1 .Lattn_nb_ok
	v_readfirstlane_b32 s100, v170
	s_lshr_b32 s100, s100, 6
	s_and_b32 s100, s100, 6
	s_sub_i32 s100, 8, s100
	v_mov_b32_e32 v62, v184
	v_mov_b32_e32 v63, v184
	v_mov_b32_e32 v116, v184
	v_mov_b32_e32 v117, v184
	v_mov_b32_e32 v114, v184
	v_mov_b32_e32 v115, v184
	v_mov_b32_e32 v112, v184
	v_mov_b32_e32 v113, v184
	s_cmp_lt_u32 s100, 3
	s_cbranch_scc1 .Lattn_nb_ok
	v_mov_b32_e32 v110, v184
	v_mov_b32_e32 v111, v184
	v_mov_b32_e32 v108, v184
	v_mov_b32_e32 v109, v184
	v_mov_b32_e32 v106, v184
	v_mov_b32_e32 v107, v184
	v_mov_b32_e32 v104, v184
	v_mov_b32_e32 v105, v184
	s_cmp_lt_u32 s100, 5
	s_cbranch_scc1 .Lattn_nb_ok
	v_mov_b32_e32 v82, v184
	v_mov_b32_e32 v83, v184
	v_mov_b32_e32 v80, v184
	v_mov_b32_e32 v81, v184
	v_mov_b32_e32 v78, v184
	v_mov_b32_e32 v79, v184
	v_mov_b32_e32 v76, v184
	v_mov_b32_e32 v77, v184
	s_cmp_lt_u32 s100, 7
	s_cbranch_scc1 .Lattn_nb_ok
	v_mov_b32_e32 v74, v184
	v_mov_b32_e32 v75, v184
	v_mov_b32_e32 v72, v184
	v_mov_b32_e32 v73, v184
	v_mov_b32_e32 v70, v184
	v_mov_b32_e32 v71, v184
	v_mov_b32_e32 v68, v184
	v_mov_b32_e32 v69, v184
; __device__ __forceinline__ void attn_phase(const Params& p, LAS unsigned char* lds, int tid, int G, int bid) {
;     ...
;                 const float v = valid ? s[tt][j] - sl2 * (float)delta : -INFINITY; s[tt][j] = v; mx = fmaxf(mx, v); }
;         mx = fmaxf(mx, __shfl_xor(mx, 16)); mx = fmaxf(mx, __shfl_xor(mx, 32));
;         float den = 0.f;
; #pragma unroll
;         for (int tt = 0; tt < 10; ++tt)
; #pragma unroll
;             for (int j = 0; j < 4; ++j) { const float e = __builtin_amdgcn_exp2f(s[tt][j] - mx); s[tt][j] = e; den += e; }
;         den += __shfl_xor(den, 16); den += __shfl_xor(den, 32);
;         f32x4 o[4];
; #pragma unroll
;         for (int dt = 0; dt < 4; ++dt) o[dt] = (f32x4){0.f, 0.f, 0.f, 0.f};
; #pragma unroll
;         for (int c = 0; c < 5; ++c) {
;             int p0_ = 0, p1_ = 0;
;             p0_ = __builtin_amdgcn_cvt_pk_fp8_f32(s[2 * c][0], s[2 * c][1], p0_, false); p0_ = __builtin_amdgcn_cvt_pk_fp8_f32(s[2 * c][2], s[2 * c][3], p0_, true);
;             p1_ = __builtin_amdgcn_cvt_pk_fp8_f32(s[2 * c + 1][0], s[2 * c + 1][1], p1_, false); p1_ = __builtin_amdgcn_cvt_pk_fp8_f32(s[2 * c + 1][2], s[2 * c + 1][3], p1_, true);
;             const long pf = (long)(((unsigned long long)(unsigned)p1_ << 32) | (unsigned long long)(unsigned)p0_);
.Lattn_nb_ok:
	s_mov_b32 s12, 0xff800000
	v_max3_f32 v118, v62, s12, v63
	v_max3_f32 v118, v118, v116, v117
	v_max3_f32 v118, v118, v114, v115
	v_max3_f32 v118, v118, v112, v113
	v_max3_f32 v118, v118, v110, v111
	v_max3_f32 v118, v118, v108, v109
	v_max3_f32 v118, v118, v106, v107
	v_max3_f32 v118, v118, v104, v105
	v_max3_f32 v118, v118, v82, v83
	v_max3_f32 v118, v118, v80, v81
	v_max3_f32 v118, v118, v78, v79
	v_max3_f32 v118, v118, v76, v77
	v_max3_f32 v118, v118, v74, v75
	v_max3_f32 v118, v118, v72, v73
	v_max3_f32 v118, v118, v70, v71
	v_max3_f32 v118, v118, v68, v69
	v_max3_f32 v118, v118, v66, v67
	v_max3_f32 v118, v118, v64, v65
	v_max3_f32 v118, v118, v60, v61
	v_max3_f32 v9, v118, v10, v11
	v_mov_b32_e32 v118, v9
	v_mov_b32_e32 v213, v9
	s_nop 1
	v_permlane16_swap_b32_e32 v118, v213
	v_max_f32_e32 v9, v118, v213
	v_mov_b32_e32 v118, v9
	v_mov_b32_e32 v213, v9
	s_nop 1
	v_permlane32_swap_b32_e32 v118, v213
	v_max_f32_e32 v9, v118, v213
	v_mul_f32_e64 v213, -v9, s80
	v_fma_f32 v62, v62, s80, v213
	v_exp_f32_e32 v62, v62
	v_fma_f32 v63, v63, s80, v213
	v_exp_f32_e32 v63, v63
	v_fma_f32 v116, v116, s80, v213
	v_exp_f32_e32 v116, v116
	v_fma_f32 v117, v117, s80, v213
	v_exp_f32_e32 v117, v117
	v_fma_f32 v114, v114, s80, v213
	v_add_f32_e32 v118, 0, v62
	v_exp_f32_e32 v114, v114
	v_fma_f32 v115, v115, s80, v213
	v_add_f32_e32 v118, v63, v118
	v_exp_f32_e32 v115, v115
	v_fma_f32 v112, v112, s80, v213
	v_add_f32_e32 v118, v116, v118
	v_exp_f32_e32 v112, v112
	v_fma_f32 v113, v113, s80, v213
	v_add_f32_e32 v118, v117, v118
	v_exp_f32_e32 v113, v113
	v_fma_f32 v110, v110, s80, v213
	v_add_f32_e32 v118, v114, v118
	v_exp_f32_e32 v110, v110
	v_fma_f32 v111, v111, s80, v213
	v_add_f32_e32 v118, v115, v118
	v_exp_f32_e32 v111, v111
	v_fma_f32 v108, v108, s80, v213
	v_add_f32_e32 v118, v112, v118
	v_exp_f32_e32 v108, v108
	v_fma_f32 v109, v109, s80, v213
	v_add_f32_e32 v118, v113, v118
	v_exp_f32_e32 v109, v109
	v_fma_f32 v106, v106, s80, v213
	v_add_f32_e32 v118, v110, v118
	v_exp_f32_e32 v106, v106
	v_fma_f32 v107, v107, s80, v213
	v_add_f32_e32 v118, v111, v118
	v_exp_f32_e32 v107, v107
	v_fma_f32 v104, v104, s80, v213
	v_add_f32_e32 v118, v108, v118
	v_exp_f32_e32 v104, v104
	v_fma_f32 v105, v105, s80, v213
	v_add_f32_e32 v118, v109, v118
	v_exp_f32_e32 v105, v105
	v_fma_f32 v82, v82, s80, v213
	v_add_f32_e32 v118, v106, v118
	v_exp_f32_e32 v82, v82
	v_fma_f32 v83, v83, s80, v213
	v_add_f32_e32 v118, v107, v118
	v_exp_f32_e32 v83, v83
	v_fma_f32 v80, v80, s80, v213
	v_add_f32_e32 v118, v104, v118
	v_exp_f32_e32 v80, v80
	v_fma_f32 v81, v81, s80, v213
	v_add_f32_e32 v118, v105, v118
	v_exp_f32_e32 v81, v81
	v_fma_f32 v78, v78, s80, v213
	v_add_f32_e32 v118, v82, v118
	v_exp_f32_e32 v78, v78
	v_fma_f32 v79, v79, s80, v213
	v_add_f32_e32 v118, v83, v118
	v_exp_f32_e32 v79, v79
	v_fma_f32 v76, v76, s80, v213
	v_add_f32_e32 v118, v80, v118
	v_exp_f32_e32 v119, v76
	v_add_f32_e32 v118, v81, v118
	v_add_f32_e32 v118, v78, v118
	v_add_f32_e32 v118, v79, v118
	v_fma_f32 v77, v77, s80, v213
	v_add_f32_e32 v76, v119, v118
	v_exp_f32_e32 v118, v77
	v_fma_f32 v74, v74, s80, v213
	v_exp_f32_e32 v186, v74
	v_fma_f32 v75, v75, s80, v213
	v_exp_f32_e32 v187, v75
	v_fma_f32 v72, v72, s80, v213
	v_exp_f32_e32 v188, v72
	v_fma_f32 v73, v73, s80, v213
	v_add_f32_e32 v76, v118, v76
	v_exp_f32_e32 v189, v73
	v_fma_f32 v70, v70, s80, v213
	v_add_f32_e32 v74, v186, v76
	v_exp_f32_e32 v190, v70
	v_fma_f32 v71, v71, s80, v213
	v_add_f32_e32 v74, v187, v74
	v_exp_f32_e32 v191, v71
	v_fma_f32 v68, v68, s80, v213
	v_add_f32_e32 v72, v188, v74
	v_exp_f32_e32 v192, v68
	v_fma_f32 v69, v69, s80, v213
	v_add_f32_e32 v72, v189, v72
	v_exp_f32_e32 v193, v69
	v_fma_f32 v66, v66, s80, v213
	v_add_f32_e32 v70, v190, v72
	v_exp_f32_e32 v194, v66
	v_fma_f32 v67, v67, s80, v213
	v_add_f32_e32 v70, v191, v70
	v_exp_f32_e32 v195, v67
	v_fma_f32 v64, v64, s80, v213
	v_add_f32_e32 v68, v192, v70
	v_exp_f32_e32 v196, v64
	v_fma_f32 v65, v65, s80, v213
	v_add_f32_e32 v68, v193, v68
	v_exp_f32_e32 v197, v65
	v_fma_f32 v60, v60, s80, v213
	v_add_f32_e32 v66, v194, v68
	v_exp_f32_e32 v198, v60
	v_fma_f32 v61, v61, s80, v213
	v_add_f32_e32 v66, v195, v66
	v_exp_f32_e32 v199, v61
	v_fma_f32 v10, v10, s80, v213
	v_add_f32_e32 v64, v196, v66
	v_exp_f32_e32 v200, v10
	v_fma_f32 v11, v11, s80, v213
	v_add_f32_e32 v64, v197, v64
	v_exp_f32_e32 v201, v11
	v_add_f32_e32 v60, v198, v64
	v_add_f32_e32 v60, v199, v60
	v_add_f32_e32 v10, v200, v60
	v_add_f32_e32 v10, v201, v10
	v_mov_b32_e32 v11, v10
	v_mov_b32_e32 v213, v10
	s_nop 1
	v_permlane16_swap_b32_e32 v11, v213
	v_add_f32_e32 v202, v11, v213
	v_cvt_pk_fp8_f32 v11, v114, v115
	v_cvt_pk_fp8_f32 v11, v112, v113 op_sel:[0,0,1]
	ds_read_b64_tr_b8 v[60:61], v246 offset:0
	ds_read_b64_tr_b8 v[64:65], v246 offset:16
	ds_read_b64_tr_b8 v[68:69], v246 offset:32
	ds_read_b64_tr_b8 v[72:73], v246 offset:48
	ds_read_b64_tr_b8 v[214:215], v246 offset:2560
	ds_read_b64_tr_b8 v[216:217], v246 offset:2576
	ds_read_b64_tr_b8 v[218:219], v246 offset:2592
	ds_read_b64_tr_b8 v[220:221], v246 offset:2608
	ds_read_b64_tr_b8 v[222:223], v246 offset:5120
	ds_read_b64_tr_b8 v[224:225], v246 offset:5136
	ds_read_b64_tr_b8 v[226:227], v246 offset:5152
	ds_read_b64_tr_b8 v[228:229], v246 offset:5168
	v_cvt_pk_fp8_f32 v10, v62, v63
	v_mov_b32_e32 v203, v202
	v_mov_b32_e32 v213, v202
	s_nop 1
	v_permlane32_swap_b32_e32 v203, v213
	v_add_f32_e32 v203, v203, v213
	v_cvt_pk_fp8_f32 v10, v116, v117 op_sel:[0,0,1]
	s_waitcnt lgkmcnt(8)
; #define LAS __attribute__((address_space(3)))
; __device__ __forceinline__ float f8c(float v) { return fminf(fmaxf(v, -448.f), 448.f); }
; #define LDS_WAIT() asm volatile("s_waitcnt lgkmcnt(0)" ::: "memory")
; __device__ __forceinline__ void attn_phase(const Params& p, LAS unsigned char* lds, int tid, int G, int bid) {
;     ...
;         for (int c = 0; c < 5; ++c) {
;             int p0_ = 0, p1_ = 0;
;             p0_ = __builtin_amdgcn_cvt_pk_fp8_f32(s[2 * c][0], s[2 * c][1], p0_, false); p0_ = __builtin_amdgcn_cvt_pk_fp8_f32(s[2 * c][2], s[2 * c][3], p0_, true);
;             p1_ = __builtin_amdgcn_cvt_pk_fp8_f32(s[2 * c + 1][0], s[2 * c + 1][1], p1_, false); p1_ = __builtin_amdgcn_cvt_pk_fp8_f32(s[2 * c + 1][2], s[2 * c + 1][3], p1_, true);
;             const long pf = (long)(((unsigned long long)(unsigned)p1_ << 32) | (unsigned long long)(unsigned)p0_);
; #pragma unroll
;             for (int dt = 0; dt < 4; ++dt) { const LAS unsigned char* vp = lds + VT_OFF + (16 * dt + fr) * VT_PITCH + 16 * (tstart + 2 * c) + 4 * quad;
;                 const unsigned lo = *(const LAS unsigned*)vp, hi = *(const LAS unsigned*)(vp + 16);
;                 const long vf = (long)(((unsigned long long)hi << 32) | (unsigned long long)lo);
;                 o[dt] = __builtin_amdgcn_mfma_f32_16x16x32_fp8_fp8(vf, pf, o[dt], 0, 0, 0); }
;         }
;         const float inv = 1.0f / den;
;         { LAS unsigned char* ost = lds + OST_OFF + w * 2304;
; #pragma unroll
;           for (int dt = 0; dt < 4; ++dt) { int wv = 0; wv = __builtin_amdgcn_cvt_pk_fp8_f32(f8c(o[dt][0] * inv), f8c(o[dt][1] * inv), wv, false); wv = __builtin_amdgcn_cvt_pk_fp8_f32(f8c(o[dt][2] * inv), f8c(o[dt][3] * inv), wv, true);
;               *(LAS unsigned*)(ost + fr * 80 + 16 * dt + 4 * quad) = (unsigned)wv; }
;           LDS_WAIT();
;           const int q2 = lane >> 2, ck = lane & 3, tq2 = ((nb * 128 + 16 * w + q2) << dsh) + r;
;           const u32x4 r0 = *(const LAS u32x4*)(ost + q2 * 80 + ck * 16);
;           unsigned char* op = (unsigned char*)OG + ((size_t)g * M + (size_t)b * SEQ + tq2) * AOW + hh * 64 + ck * 16;
;           *(u32x4*)op = r0; }
;         if (quad == 0) LSE[(size_t)uid * 128 + qi] = (mx + __builtin_amdgcn_logf(den)) * LN2F;
	s_nop 0
	v_mfma_f32_16x16x32_fp8_fp8 v[60:63], v[60:61], v[10:11], 0
	v_mfma_f32_16x16x32_fp8_fp8 v[64:67], v[64:65], v[10:11], 0
	v_mfma_f32_16x16x32_fp8_fp8 v[68:71], v[68:69], v[10:11], 0
	v_mfma_f32_16x16x32_fp8_fp8 v[72:75], v[72:73], v[10:11], 0
	ds_read_b64_tr_b8 v[230:231], v246 offset:7680
	ds_read_b64_tr_b8 v[232:233], v246 offset:7696
	ds_read_b64_tr_b8 v[234:235], v246 offset:7712
	ds_read_b64_tr_b8 v[236:237], v246 offset:7728
	v_cvt_pk_fp8_f32 v10, v110, v111
	v_cvt_pk_fp8_f32 v11, v106, v107
	v_cvt_pk_fp8_f32 v10, v108, v109 op_sel:[0,0,1]
	v_cvt_pk_fp8_f32 v11, v104, v105 op_sel:[0,0,1]
	s_waitcnt lgkmcnt(8)
	s_nop 0
	v_mfma_f32_16x16x32_fp8_fp8 v[60:63], v[214:215], v[10:11], v[60:63]
	v_mfma_f32_16x16x32_fp8_fp8 v[64:67], v[216:217], v[10:11], v[64:67]
	v_mfma_f32_16x16x32_fp8_fp8 v[68:71], v[218:219], v[10:11], v[68:71]
	v_mfma_f32_16x16x32_fp8_fp8 v[72:75], v[220:221], v[10:11], v[72:75]
	ds_read_b64_tr_b8 v[238:239], v246 offset:10240
	ds_read_b64_tr_b8 v[240:241], v246 offset:10256
	ds_read_b64_tr_b8 v[242:243], v246 offset:10272
	ds_read_b64_tr_b8 v[244:245], v246 offset:10288
	v_cvt_pk_fp8_f32 v10, v82, v83
	v_cvt_pk_fp8_f32 v11, v78, v79
	v_cvt_pk_fp8_f32 v10, v80, v81 op_sel:[0,0,1]
	v_cvt_pk_fp8_f32 v11, v119, v118 op_sel:[0,0,1]
	s_waitcnt lgkmcnt(8)
	s_nop 0
	v_mfma_f32_16x16x32_fp8_fp8 v[60:63], v[222:223], v[10:11], v[60:63]
	v_mfma_f32_16x16x32_fp8_fp8 v[64:67], v[224:225], v[10:11], v[64:67]
	v_mfma_f32_16x16x32_fp8_fp8 v[68:71], v[226:227], v[10:11], v[68:71]
	v_mfma_f32_16x16x32_fp8_fp8 v[72:75], v[228:229], v[10:11], v[72:75]
	v_cvt_pk_fp8_f32 v10, v186, v187
	v_cvt_pk_fp8_f32 v11, v190, v191
	v_cvt_pk_fp8_f32 v10, v188, v189 op_sel:[0,0,1]
	v_cvt_pk_fp8_f32 v11, v192, v193 op_sel:[0,0,1]
	s_waitcnt lgkmcnt(4)
	s_nop 0
	v_mfma_f32_16x16x32_fp8_fp8 v[60:63], v[230:231], v[10:11], v[60:63]
	v_mfma_f32_16x16x32_fp8_fp8 v[64:67], v[232:233], v[10:11], v[64:67]
	v_mfma_f32_16x16x32_fp8_fp8 v[68:71], v[234:235], v[10:11], v[68:71]
	v_mfma_f32_16x16x32_fp8_fp8 v[72:75], v[236:237], v[10:11], v[72:75]
	v_cvt_pk_fp8_f32 v10, v194, v195
	v_cvt_pk_fp8_f32 v11, v198, v199
	v_cvt_pk_fp8_f32 v10, v196, v197 op_sel:[0,0,1]
	v_cvt_pk_fp8_f32 v11, v200, v201 op_sel:[0,0,1]
	s_waitcnt lgkmcnt(0)
	s_nop 0
	v_mfma_f32_16x16x32_fp8_fp8 v[60:63], v[238:239], v[10:11], v[60:63]
	v_mfma_f32_16x16x32_fp8_fp8 v[76:79], v[240:241], v[10:11], v[64:67]
	v_mfma_f32_16x16x32_fp8_fp8 v[214:217], v[242:243], v[10:11], v[68:71]
	v_mfma_f32_16x16x32_fp8_fp8 v[218:221], v[244:245], v[10:11], v[72:75]
	s_nop 7
	v_mov_b32_e32 v64, v203
	v_div_scale_f32 v10, s[6:7], v64, v64, 1.0
	v_rcp_f32_e32 v11, v10
	s_nop 0
	v_fma_f32 v65, -v10, v11, 1.0
	v_fmac_f32_e32 v11, v65, v11
	v_div_scale_f32 v65, vcc, 1.0, v64, 1.0
	v_mul_f32_e32 v74, v65, v11
	v_fma_f32 v75, -v10, v74, v65
	v_fmac_f32_e32 v74, v75, v11
	v_fma_f32 v10, -v10, v74, v65
	v_div_fmas_f32 v10, v10, v11, v74
	v_div_fixup_f32 v10, v10, v64, 1.0
	v_mul_f32_e32 v11, v10, v60
	v_mul_f32_e32 v60, v10, v61
	v_med3_f32 v11, v11, s81, v185
	v_med3_f32 v60, v60, s81, v185
	v_cvt_pk_fp8_f32 v61, v11, v60
	v_mul_f32_e32 v11, v10, v62
	v_mul_f32_e32 v60, v10, v63
	v_med3_f32 v11, v11, s81, v185
	v_med3_f32 v60, v60, s81, v185
	v_cvt_pk_fp8_f32 v61, v11, v60 op_sel:[0,0,1]
	v_mul_f32_e32 v11, v10, v76
	v_mul_f32_e32 v60, v10, v77
	v_med3_f32 v11, v11, s81, v185
	v_med3_f32 v60, v60, s81, v185
	v_cvt_pk_fp8_f32 v62, v11, v60
	v_mul_f32_e32 v11, v10, v78
	v_mul_f32_e32 v60, v10, v79
	v_med3_f32 v11, v11, s81, v185
	v_med3_f32 v60, v60, s81, v185
	v_cvt_pk_fp8_f32 v62, v11, v60 op_sel:[0,0,1]
	v_mul_f32_e32 v11, v10, v214
	v_mul_f32_e32 v60, v10, v215
	v_med3_f32 v11, v11, s81, v185
	ds_write2_b32 v181, v61, v62 offset1:4
	v_med3_f32 v60, v60, s81, v185
	v_cvt_pk_fp8_f32 v61, v11, v60
	v_mul_f32_e32 v11, v10, v216
	v_mul_f32_e32 v60, v10, v217
	v_med3_f32 v11, v11, s81, v185
	v_med3_f32 v60, v60, s81, v185
	v_cvt_pk_fp8_f32 v61, v11, v60 op_sel:[0,0,1]
	v_mul_f32_e32 v11, v10, v218
	v_mul_f32_e32 v60, v10, v219
	v_med3_f32 v11, v11, s81, v185
	v_med3_f32 v60, v60, s81, v185
	v_cvt_pk_fp8_f32 v62, v11, v60
	v_mul_f32_e32 v11, v10, v220
	v_mul_f32_e32 v10, v10, v221
	v_med3_f32 v11, v11, s81, v185
	v_med3_f32 v10, v10, s81, v185
	v_cvt_pk_fp8_f32 v62, v11, v10 op_sel:[0,0,1]
	v_lshl_add_u32 v10, s86, 7, v124
	v_lshlrev_b32_e32 v10, s1, v10
	v_add_u32_e32 v10, s5, v10
	s_ashr_i32 s5, s4, 31
	s_ashr_i32 s1, s0, 31
	s_lshl_b64 s[4:5], s[4:5], 15
	s_lshl_b64 s[0:1], s[0:1], 11
	ds_write2_b32 v181, v61, v62 offset0:8 offset1:12
	s_add_u32 s0, s4, s0
	s_waitcnt lgkmcnt(0)
	s_addc_u32 s1, s5, s1
	v_ashrrev_i32_e32 v11, 31, v10
	ds_read_b128 v[60:63], v182
	v_lshl_add_u64 v[10:11], s[0:1], 0, v[10:11]
	v_lshlrev_b64 v[10:11], 8, v[10:11]
	v_lshl_add_u64 v[10:11], s[94:95], 0, v[10:11]
	s_lshl_b32 s86, s11, 6
	v_lshl_add_u64 v[10:11], v[10:11], 0, s[86:87]
	v_lshl_add_u64 v[10:11], v[10:11], 0, v[84:85]
	s_waitcnt lgkmcnt(0)
	global_store_dwordx4 v[10:11], v[60:63], off
	s_mov_b64 s[0:1], exec
	v_readlane_b32 s4, v250, 35
	v_readlane_b32 s5, v250, 36
	s_and_b64 s[4:5], s[0:1], s[4:5]
	s_mov_b64 exec, s[4:5]
	s_cbranch_execz .LBB0_286
	v_log_f32_e32 v10, v64
	s_nop 0
	v_fma_f32 v9, v9, s80, v10
	v_mul_f32_e32 v9, 0x3f317218, v9
	global_store_dword v[98:99], v9, off
